# LV: V-fragment LDS reads in the diff/FoX/window PV sections issued one MFMA earlier into spare registers; section lgkmcnt waits re-derived by in-order simulation
# baseline (speedup 1.0000x reference)
.LBB0_672:
	s_nop 7
	v_exp_f32_e32 v2, v48
	v_exp_f32_e32 v3, v49
	v_exp_f32_e32 v4, v50
	v_exp_f32_e32 v5, v51
	v_add_f32_e32 v0, 0, v2
	v_exp_f32_e32 v6, v52
	v_add_f32_e32 v0, v3, v0
	v_exp_f32_e32 v7, v53
	v_add_f32_e32 v0, v4, v0
	v_exp_f32_e32 v8, v54
	v_add_f32_e32 v0, v5, v0
	v_exp_f32_e32 v9, v55
	v_add_f32_e32 v0, v6, v0
	v_add_f32_e32 v0, v7, v0
	v_exp_f32_e32 v50, v60
	v_exp_f32_e32 v60, v70
	v_add3_u32 v70, s6, v143, v145
	v_add_f32_e32 v0, v8, v0
	v_exp_f32_e32 v51, v61
	v_exp_f32_e32 v61, v71
	v_add_u32_e32 v71, 0x2000, v70
	v_add_f32_e32 v0, v9, v0
	v_cvt_pk_bf16_f32 v2, v2, v3
	v_cvt_pk_bf16_f32 v3, v4, v5
	v_cvt_pk_bf16_f32 v4, v6, v7
	v_cvt_pk_bf16_f32 v5, v8, v9
	ds_read2_b64 v[6:9], v71 offset0:128 offset1:130
	ds_read2_b64 v[10:13], v71 offset0:132 offset1:134
	v_add_u32_e32 v70, 0x3000, v70
	ds_read2_b64 v[236:239], v70 offset0:160 offset1:162
	s_waitcnt lgkmcnt(2)
	v_mfma_f32_32x32x16_bf16 v[32:47], v[6:9], v[2:5], v[32:47]
	s_mul_i32 s16, s4, 0x4a00
	v_or_b32_e32 v252, s16, v125
	v_add_u32_e32 v253, v252, v137
	s_waitcnt vmcnt(3)
	ds_write_b128 v253, v[100:103]
	global_load_dwordx4 v[100:103], v228, s[10:11]
	v_exp_f32_e32 v14, v56
	v_exp_f32_e32 v15, v57
	v_exp_f32_e32 v48, v58
	v_exp_f32_e32 v49, v59
	v_exp_f32_e32 v52, v62
	v_exp_f32_e32 v53, v63
	ds_read2_b64 v[240:243], v70 offset0:164 offset1:166
	s_waitcnt lgkmcnt(2)
	v_mfma_f32_32x32x16_bf16 v[16:31], v[236:239], v[2:5], v[16:31]
	v_add3_u32 v253, v252, v138, s33
	s_waitcnt vmcnt(2)
	ds_write2_b64 v253, v[104:105], v[106:107] offset1:1
	global_load_dwordx4 v[104:107], v230, s[22:23]
	v_cvt_pk_bf16_f32 v2, v14, v15
	v_cvt_pk_bf16_f32 v3, v48, v49
	v_cvt_pk_bf16_f32 v4, v50, v51
	v_cvt_pk_bf16_f32 v5, v52, v53
	v_exp_f32_e32 v54, v64
	v_exp_f32_e32 v55, v65
	s_waitcnt lgkmcnt(1)
	v_mfma_f32_32x32x16_bf16 v[16:31], v[240:243], v[2:5], v[16:31]
	ds_read2_b64 v[6:9], v71 offset0:136 offset1:138
	v_add_u32_e32 v253, v252, v139
	s_waitcnt vmcnt(3)
	ds_write_b128 v253, v[108:111]
	global_load_dwordx4 v[108:111], v229, s[10:11]
	v_exp_f32_e32 v56, v66
	v_exp_f32_e32 v57, v67
	v_exp_f32_e32 v58, v68
	v_exp_f32_e32 v59, v69
	v_add_f32_e32 v0, v14, v0
	v_add_f32_e32 v0, v15, v0
	v_mfma_f32_32x32x16_bf16 v[32:47], v[10:13], v[2:5], v[32:47]
	v_add3_u32 v253, v252, v140, s33
	s_waitcnt vmcnt(3)
	ds_write2_b64 v253, v[112:113], v[114:115] offset1:1
	global_load_dwordx4 v[112:115], v231, s[22:23]
	s_add_u32 s10, s10, 0x2000
	s_addc_u32 s11, s11, 0
	s_add_u32 s22, s22, 0x80
	s_addc_u32 s23, s23, 0
	v_cvt_pk_bf16_f32 v2, v54, v55
	v_cvt_pk_bf16_f32 v3, v56, v57
	v_cvt_pk_bf16_f32 v4, v58, v59
	v_cvt_pk_bf16_f32 v5, v60, v61
	v_add_f32_e32 v0, v48, v0
	v_add_f32_e32 v0, v49, v0
	v_exp_f32_e32 v62, v72
	ds_read2_b64 v[244:247], v70 offset0:168 offset1:170
	s_waitcnt lgkmcnt(3)
	v_mfma_f32_32x32x16_bf16 v[32:47], v[6:9], v[2:5], v[32:47]
	v_exp_f32_e32 v63, v73
	v_exp_f32_e32 v64, v74
	v_exp_f32_e32 v65, v75
	v_exp_f32_e32 v66, v76
	v_exp_f32_e32 v67, v77
	v_exp_f32_e32 v68, v78
	ds_read2_b64 v[248:251], v71 offset0:140 offset1:142
	s_waitcnt lgkmcnt(1)
	v_mfma_f32_32x32x16_bf16 v[16:31], v[244:247], v[2:5], v[16:31]
	v_exp_f32_e32 v69, v79
	v_add_f32_e32 v0, v50, v0
	v_add_f32_e32 v0, v51, v0
	v_add_f32_e32 v0, v52, v0
	v_add_f32_e32 v0, v53, v0
	v_cvt_pk_bf16_f32 v2, v62, v63
	v_cvt_pk_bf16_f32 v3, v64, v65
	v_cvt_pk_bf16_f32 v4, v66, v67
	v_cvt_pk_bf16_f32 v5, v68, v69
	v_add_f32_e32 v0, v54, v0
	v_add_f32_e32 v0, v55, v0
	ds_read2_b64 v[236:239], v70 offset0:172 offset1:174
	s_waitcnt lgkmcnt(1)
	v_mfma_f32_32x32x16_bf16 v[32:47], v[248:251], v[2:5], v[32:47]
	v_add_f32_e32 v0, v56, v0
	v_add_f32_e32 v0, v57, v0
	v_add_f32_e32 v0, v58, v0
	v_add_f32_e32 v0, v59, v0
	v_add_f32_e32 v0, v60, v0
	v_add_f32_e32 v0, v61, v0
	v_add_f32_e32 v0, v62, v0
	v_add_f32_e32 v0, v63, v0
	s_waitcnt lgkmcnt(0)
	v_mfma_f32_32x32x16_bf16 v[16:31], v[236:239], v[2:5], v[16:31]
	s_and_saveexec_b64 s[0:1], s[38:39]
	s_cbranch_execz .Ld5f_noga
	s_waitcnt vmcnt(4)
	v_xor_b32_e32 v239, 0x80000000, v99
	v_xor_b32_e32 v238, 0x80000000, v98
	v_xor_b32_e32 v237, 0x80000000, v97
	v_xor_b32_e32 v236, 0x80000000, v96
	v_add_u32_e32 v253, s16, v119
	ds_write_b128 v253, v[236:239] offset:18432
	global_load_dwordx4 v[96:99], v228, s[24:25]

.LBB0_705:
	s_nop 7
	v_exp_f32_e32 v2, v80
	v_exp_f32_e32 v3, v81
	v_exp_f32_e32 v4, v82
	v_exp_f32_e32 v5, v83
	v_add_f32_e32 v0, 0, v2
	v_exp_f32_e32 v6, v84
	v_add_f32_e32 v0, v3, v0
	v_exp_f32_e32 v7, v85
	v_add_f32_e32 v0, v4, v0
	v_exp_f32_e32 v8, v86
	v_add_f32_e32 v0, v5, v0
	v_exp_f32_e32 v9, v87
	v_add_f32_e32 v0, v6, v0
	v_add_f32_e32 v0, v7, v0
	v_add3_u32 v86, s14, v147, v149
	v_add_f32_e32 v0, v8, v0
	v_add_u32_e32 v87, 0x2000, v86
	v_add_f32_e32 v0, v9, v0
	v_cvt_pk_bf16_f32 v2, v2, v3
	v_cvt_pk_bf16_f32 v3, v4, v5
	v_cvt_pk_bf16_f32 v4, v6, v7
	v_cvt_pk_bf16_f32 v5, v8, v9
	ds_read2_b64 v[6:9], v87 offset0:128 offset1:130
	ds_read2_b64 v[10:13], v87 offset0:132 offset1:134
	v_add_u32_e32 v86, 0x3000, v86
	ds_read2_b64 v[236:239], v86 offset0:160 offset1:162
	s_waitcnt lgkmcnt(2)
	v_mfma_f32_32x32x16_bf16 v[32:47], v[6:9], v[2:5], v[32:47]
	s_mul_i32 s1, s9, 0x4a00
	v_or_b32_e32 v184, s1, v131
	v_add_u32_e32 v185, v184, v133
	s_waitcnt vmcnt(3)
	ds_write_b128 v185, v[108:111]
	global_load_dwordx4 v[108:111], v180, s[10:11]
	v_exp_f32_e32 v14, v88
	v_exp_f32_e32 v15, v89
	v_exp_f32_e32 v80, v90
	v_exp_f32_e32 v81, v91
	v_exp_f32_e32 v82, v92
	v_exp_f32_e32 v83, v93
	ds_read2_b64 v[240:243], v86 offset0:164 offset1:166
	s_waitcnt lgkmcnt(2)
	v_mfma_f32_32x32x16_bf16 v[16:31], v[236:239], v[2:5], v[16:31]
	v_add3_u32 v185, v184, v144, s33
	s_waitcnt vmcnt(2)
	ds_write2_b64 v185, v[104:105], v[106:107] offset1:1
	global_load_dwordx4 v[104:107], v182, s[16:17]
	v_exp_f32_e32 v84, v94
	v_exp_f32_e32 v85, v95
	v_cvt_pk_bf16_f32 v2, v14, v15
	v_cvt_pk_bf16_f32 v3, v80, v81
	v_cvt_pk_bf16_f32 v4, v82, v83
	v_cvt_pk_bf16_f32 v5, v84, v85
	v_exp_f32_e32 v64, v64
	v_exp_f32_e32 v65, v65
	s_waitcnt lgkmcnt(1)
	v_mfma_f32_32x32x16_bf16 v[16:31], v[240:243], v[2:5], v[16:31]
	ds_read2_b64 v[6:9], v87 offset0:136 offset1:138
	v_add_u32_e32 v185, v184, v145
	s_waitcnt vmcnt(3)
	ds_write_b128 v185, v[112:115]
	global_load_dwordx4 v[112:115], v181, s[10:11]
	v_exp_f32_e32 v66, v66
	v_exp_f32_e32 v67, v67
	v_exp_f32_e32 v68, v68
	v_exp_f32_e32 v69, v69
	v_exp_f32_e32 v70, v70
	v_exp_f32_e32 v71, v71
	v_mfma_f32_32x32x16_bf16 v[32:47], v[10:13], v[2:5], v[32:47]
	v_add3_u32 v185, v184, v146, s33
	s_waitcnt vmcnt(3)
	ds_write2_b64 v185, v[116:117], v[118:119] offset1:1
	global_load_dwordx4 v[116:119], v183, s[16:17]
	s_add_u32 s10, s10, 0x2000
	s_addc_u32 s11, s11, 0
	s_add_u32 s16, s16, 0x80
	s_addc_u32 s17, s17, 0
	v_cvt_pk_bf16_f32 v2, v64, v65
	v_cvt_pk_bf16_f32 v3, v66, v67
	v_cvt_pk_bf16_f32 v4, v68, v69
	v_cvt_pk_bf16_f32 v5, v70, v71
	v_add_f32_e32 v0, v14, v0
	v_add_f32_e32 v0, v15, v0
	v_add_f32_e32 v0, v80, v0
	ds_read2_b64 v[244:247], v86 offset0:168 offset1:170
	s_waitcnt lgkmcnt(3)
	v_mfma_f32_32x32x16_bf16 v[32:47], v[6:9], v[2:5], v[32:47]
	v_add_f32_e32 v0, v81, v0
	v_exp_f32_e32 v72, v72
	v_exp_f32_e32 v73, v73
	v_exp_f32_e32 v74, v74
	v_exp_f32_e32 v75, v75
	v_exp_f32_e32 v76, v76
	ds_read2_b64 v[248:251], v87 offset0:140 offset1:142
	s_waitcnt lgkmcnt(1)
	v_mfma_f32_32x32x16_bf16 v[16:31], v[244:247], v[2:5], v[16:31]
	v_exp_f32_e32 v77, v77
	v_exp_f32_e32 v78, v78
	v_exp_f32_e32 v79, v79
	v_add_f32_e32 v0, v82, v0
	v_add_f32_e32 v0, v83, v0
	v_add_f32_e32 v0, v84, v0
	v_add_f32_e32 v0, v85, v0
	v_cvt_pk_bf16_f32 v2, v72, v73
	v_cvt_pk_bf16_f32 v3, v74, v75
	v_cvt_pk_bf16_f32 v4, v76, v77
	v_cvt_pk_bf16_f32 v5, v78, v79
	v_add_f32_e32 v0, v64, v0
	v_add_f32_e32 v0, v65, v0
	ds_read2_b64 v[236:239], v86 offset0:172 offset1:174
	s_waitcnt lgkmcnt(1)
	v_mfma_f32_32x32x16_bf16 v[32:47], v[248:251], v[2:5], v[32:47]
	v_add_f32_e32 v0, v66, v0
	v_add_f32_e32 v0, v67, v0
	v_add_f32_e32 v0, v68, v0
	v_add_f32_e32 v0, v69, v0
	v_add_f32_e32 v0, v70, v0
	v_add_f32_e32 v0, v71, v0
	v_add_f32_e32 v0, v72, v0
	v_add_f32_e32 v0, v73, v0
	s_waitcnt lgkmcnt(0)
	v_mfma_f32_32x32x16_bf16 v[16:31], v[236:239], v[2:5], v[16:31]
	v_add_f32_e32 v0, v74, v0
	v_add_f32_e32 v0, v75, v0
	v_add_f32_e32 v0, v76, v0
	v_add_f32_e32 v0, v77, v0
	v_add_f32_e32 v0, v78, v0
	v_add_f32_e32 v0, v79, v0
	v_add_f32_e32 v152, v152, v0
	v_cmp_lt_f32_e32 vcc, s20, v0
	s_cbranch_vccz .LBB0_707
	v_mov_b32_e32 v2, v0
	s_nop 1
	v_permlane32_swap_b32_e32 v0, v2
	v_add_f32_e32 v0, v0, v2
	v_log_f32_e32 v2, v0
	v_cmp_lt_f32_e32 vcc, s20, v0
	s_nop 1
	v_cndmask_b32_e32 v2, 0, v2, vcc
	v_exp_f32_e64 v0, -v2
	v_add_f32_e32 v153, v153, v2
	v_xor_b32_e32 v63, 0x80000000, v153
	v_mov_b32_e32 v62, v63
	v_mul_f32_e32 v152, v152, v0
	v_pk_mul_f32 v[46:47], v[46:47], v[0:1] op_sel_hi:[1,0]
	v_pk_mul_f32 v[44:45], v[44:45], v[0:1] op_sel_hi:[1,0]
	v_pk_mul_f32 v[42:43], v[42:43], v[0:1] op_sel_hi:[1,0]
	v_pk_mul_f32 v[40:41], v[40:41], v[0:1] op_sel_hi:[1,0]
	v_pk_mul_f32 v[38:39], v[38:39], v[0:1] op_sel_hi:[1,0]
	v_pk_mul_f32 v[36:37], v[36:37], v[0:1] op_sel_hi:[1,0]
	v_pk_mul_f32 v[34:35], v[34:35], v[0:1] op_sel_hi:[1,0]
	v_pk_mul_f32 v[32:33], v[32:33], v[0:1] op_sel_hi:[1,0]
	v_pk_mul_f32 v[30:31], v[30:31], v[0:1] op_sel_hi:[1,0]
	v_pk_mul_f32 v[28:29], v[28:29], v[0:1] op_sel_hi:[1,0]
	v_pk_mul_f32 v[26:27], v[26:27], v[0:1] op_sel_hi:[1,0]
	v_pk_mul_f32 v[24:25], v[24:25], v[0:1] op_sel_hi:[1,0]
	v_pk_mul_f32 v[22:23], v[22:23], v[0:1] op_sel_hi:[1,0]
	v_pk_mul_f32 v[20:21], v[20:21], v[0:1] op_sel_hi:[1,0]
	v_pk_mul_f32 v[18:19], v[18:19], v[0:1] op_sel_hi:[1,0]
	v_pk_mul_f32 v[16:17], v[16:17], v[0:1] op_sel_hi:[1,0]
	v_mov_b32_e32 v61, v63
	v_mov_b32_e32 v60, v63
	v_mov_b32_e32 v59, v63
	v_mov_b32_e32 v58, v63
	v_mov_b32_e32 v57, v63
	v_mov_b32_e32 v56, v63
	v_mov_b32_e32 v55, v63
	v_mov_b32_e32 v54, v63
	v_mov_b32_e32 v53, v63
	v_mov_b32_e32 v52, v63
	v_mov_b32_e32 v51, v63
	v_mov_b32_e32 v50, v63
	v_mov_b32_e32 v49, v63
	v_mov_b32_e32 v48, v63
	s_branch .LBB0_707

.LBB0_936:
	s_nop 4
	v_exp_f32_e32 v66, v66
	v_exp_f32_e32 v67, v67
	v_exp_f32_e32 v68, v68
	v_exp_f32_e32 v69, v69
	v_add_f32_e32 v138, 0, v66
	v_exp_f32_e32 v70, v70
	v_add_f32_e32 v138, v67, v138
	v_exp_f32_e32 v71, v71
	v_add_f32_e32 v138, v68, v138
	v_exp_f32_e32 v72, v72
	v_add_f32_e32 v138, v69, v138
	v_exp_f32_e32 v73, v73
	v_add_f32_e32 v138, v70, v138
	v_exp_f32_e32 v74, v74
	v_add_f32_e32 v138, v71, v138
	v_exp_f32_e32 v75, v75
	v_add_f32_e32 v138, v72, v138
	v_exp_f32_e32 v76, v76
	v_add_f32_e32 v138, v73, v138
	v_exp_f32_e32 v77, v77
	v_add_f32_e32 v138, v74, v138
	v_exp_f32_e32 v78, v78
	v_add_f32_e32 v138, v75, v138
	v_exp_f32_e32 v79, v79
	v_add_f32_e32 v138, v76, v138
	v_exp_f32_e32 v80, v80
	v_add_f32_e32 v138, v77, v138
	v_exp_f32_e32 v81, v81
	v_add_f32_e32 v138, v78, v138
	v_exp_f32_e32 v139, v50
	v_add_f32_e32 v138, v79, v138
	v_add_f32_e32 v138, v80, v138
	v_add_f32_e32 v138, v81, v138
	v_add_f32_e32 v50, v139, v138
	v_exp_f32_e32 v138, v52
	v_cvt_pk_bf16_f32 v52, v66, v67
	v_add3_u32 v66, s16, v181, v187
	v_add_u32_e32 v67, 0x2000, v66
	v_exp_f32_e32 v143, v56
	v_exp_f32_e32 v144, v57
	v_exp_f32_e32 v145, v58
	v_exp_f32_e32 v147, v59
	v_exp_f32_e32 v148, v60
	v_exp_f32_e32 v149, v61
	v_exp_f32_e32 v150, v62
	v_exp_f32_e32 v151, v63
	ds_read2_b64 v[56:59], v67 offset0:128 offset1:130
	ds_read2_b64 v[60:63], v67 offset0:132 offset1:134
	v_exp_f32_e32 v140, v53
	v_exp_f32_e32 v141, v54
	v_exp_f32_e32 v142, v55
	v_cvt_pk_bf16_f32 v53, v68, v69
	v_cvt_pk_bf16_f32 v54, v70, v71
	v_cvt_pk_bf16_f32 v55, v72, v73
	v_add_u32_e32 v66, 0x3000, v66
	v_exp_f32_e32 v51, v51
	ds_read2_b64 v[236:239], v66 offset0:160 offset1:162
	s_waitcnt lgkmcnt(2)
	v_mfma_f32_32x32x16_bf16 v[18:33], v[56:59], v[52:55], v[18:33]
	s_mul_i32 s22, s15, 0x4a00
	v_or_b32_e32 v252, s22, v129
	v_add_u32_e32 v253, v252, v131
	s_waitcnt vmcnt(3)
	ds_write_b128 v253, v[98:101]
	global_load_dwordx4 v[98:101], v228, s[12:13]
	v_exp_f32_e32 v64, v64
	v_exp_f32_e32 v65, v65
	v_add_f32_e32 v50, v51, v50
	v_add_f32_e32 v50, v138, v50
	v_add_f32_e32 v50, v140, v50
	v_add_f32_e32 v50, v141, v50
	ds_read2_b64 v[240:243], v66 offset0:164 offset1:166
	s_waitcnt lgkmcnt(2)
	v_mfma_f32_32x32x16_bf16 v[2:17], v[236:239], v[52:55], v[2:17]
	v_add3_u32 v253, v252, v185, s33
	s_waitcnt vmcnt(2)
	ds_write2_b64 v253, v[102:103], v[104:105] offset1:1
	global_load_dwordx4 v[102:105], v230, s[24:25]
	v_cvt_pk_bf16_f32 v52, v74, v75
	v_cvt_pk_bf16_f32 v53, v76, v77
	v_cvt_pk_bf16_f32 v54, v78, v79
	v_cvt_pk_bf16_f32 v55, v80, v81
	v_add_f32_e32 v50, v142, v50
	v_add_f32_e32 v50, v143, v50
	s_waitcnt lgkmcnt(1)
	v_mfma_f32_32x32x16_bf16 v[2:17], v[240:243], v[52:55], v[2:17]
	ds_read2_b64 v[56:59], v67 offset0:136 offset1:138
	v_add_u32_e32 v253, v252, v180
	s_waitcnt vmcnt(3)
	ds_write_b128 v253, v[106:109]
	global_load_dwordx4 v[106:109], v229, s[12:13]
	v_add_f32_e32 v50, v144, v50
	v_add_f32_e32 v50, v145, v50
	v_add_f32_e32 v50, v147, v50
	v_add_f32_e32 v50, v148, v50
	v_add_f32_e32 v50, v149, v50
	v_add_f32_e32 v50, v150, v50
	v_mfma_f32_32x32x16_bf16 v[18:33], v[60:63], v[52:55], v[18:33]
	v_add3_u32 v253, v252, v186, s33
	s_waitcnt vmcnt(3)
	ds_write2_b64 v253, v[110:111], v[112:113] offset1:1
	global_load_dwordx4 v[110:113], v231, s[24:25]
	s_add_u32 s12, s12, 0x2000
	s_addc_u32 s13, s13, 0
	s_add_u32 s24, s24, 0x80
	s_addc_u32 s25, s25, 0
	v_cvt_pk_bf16_f32 v52, v139, v51
	v_cvt_pk_bf16_f32 v53, v138, v140
	v_cvt_pk_bf16_f32 v54, v141, v142
	v_cvt_pk_bf16_f32 v55, v143, v144
	v_add_f32_e32 v50, v151, v50
	v_add_f32_e32 v50, v64, v50
	v_add_f32_e32 v50, v65, v50
	ds_read2_b64 v[244:247], v66 offset0:168 offset1:170
	s_waitcnt lgkmcnt(3)
	v_mfma_f32_32x32x16_bf16 v[18:33], v[56:59], v[52:55], v[18:33]
	v_add_f32_e32 v136, v136, v50
	v_cmp_lt_f32_e32 vcc, s20, v50
	ds_read2_b64 v[248:251], v67 offset0:140 offset1:142
	s_waitcnt lgkmcnt(1)
	v_mfma_f32_32x32x16_bf16 v[2:17], v[244:247], v[52:55], v[2:17]
	v_cvt_pk_bf16_f32 v52, v145, v147
	v_cvt_pk_bf16_f32 v53, v148, v149
	v_cvt_pk_bf16_f32 v54, v150, v151
	v_cvt_pk_bf16_f32 v55, v64, v65
	s_waitcnt lgkmcnt(0)
	s_nop 0
	ds_read2_b64 v[236:239], v66 offset0:172 offset1:174
	v_mfma_f32_32x32x16_bf16 v[18:33], v[248:251], v[52:55], v[18:33]
	s_waitcnt lgkmcnt(0)
	v_mfma_f32_32x32x16_bf16 v[2:17], v[236:239], v[52:55], v[2:17]
	s_cbranch_vccz .LBB0_938
	v_mov_b32_e32 v34, v50
	s_nop 1
	v_permlane32_swap_b32_e32 v50, v34
	v_add_f32_e32 v34, v50, v34
	v_log_f32_e32 v35, v34
	v_cmp_lt_f32_e32 vcc, s20, v34
	s_nop 1
	v_cndmask_b32_e32 v35, 0, v35, vcc
	v_exp_f32_e64 v34, -v35
	v_add_f32_e32 v0, v0, v35
	v_xor_b32_e32 v49, 0x80000000, v0
	v_mov_b32_e32 v48, v49
	v_mul_f32_e32 v136, v136, v34
	v_pk_mul_f32 v[32:33], v[32:33], v[34:35] op_sel_hi:[1,0]
	v_pk_mul_f32 v[30:31], v[30:31], v[34:35] op_sel_hi:[1,0]
	v_pk_mul_f32 v[28:29], v[28:29], v[34:35] op_sel_hi:[1,0]
	v_pk_mul_f32 v[26:27], v[26:27], v[34:35] op_sel_hi:[1,0]
	v_pk_mul_f32 v[24:25], v[24:25], v[34:35] op_sel_hi:[1,0]
	v_pk_mul_f32 v[22:23], v[22:23], v[34:35] op_sel_hi:[1,0]
	v_pk_mul_f32 v[20:21], v[20:21], v[34:35] op_sel_hi:[1,0]
	v_pk_mul_f32 v[18:19], v[18:19], v[34:35] op_sel_hi:[1,0]
	v_pk_mul_f32 v[16:17], v[16:17], v[34:35] op_sel_hi:[1,0]
	v_pk_mul_f32 v[14:15], v[14:15], v[34:35] op_sel_hi:[1,0]
	v_pk_mul_f32 v[12:13], v[12:13], v[34:35] op_sel_hi:[1,0]
	v_pk_mul_f32 v[10:11], v[10:11], v[34:35] op_sel_hi:[1,0]
	v_pk_mul_f32 v[8:9], v[8:9], v[34:35] op_sel_hi:[1,0]
	v_pk_mul_f32 v[6:7], v[6:7], v[34:35] op_sel_hi:[1,0]
	v_pk_mul_f32 v[4:5], v[4:5], v[34:35] op_sel_hi:[1,0]
	v_pk_mul_f32 v[2:3], v[2:3], v[34:35] op_sel_hi:[1,0]
	v_mov_b32_e32 v47, v49
	v_mov_b32_e32 v46, v49
	v_mov_b32_e32 v45, v49
	v_mov_b32_e32 v44, v49
	v_mov_b32_e32 v43, v49
	v_mov_b32_e32 v42, v49
	v_mov_b32_e32 v41, v49
	v_mov_b32_e32 v40, v49
	v_mov_b32_e32 v39, v49
	v_mov_b32_e32 v38, v49
	v_mov_b32_e32 v37, v49
	v_mov_b32_e32 v36, v49
	v_mov_b32_e32 v35, v49
	v_mov_b32_e32 v34, v49
	s_branch .LBB0_938
